# v42 + BAR2: in-loop grid barriers wait on the cross-XCC generation word only; XCC leaders skip the per-XCC generation bump
# baseline (speedup 1.0000x reference)
; __device__ __forceinline__ unsigned xb_ld(unsigned* p)              { return __hip_atomic_load(p, __ATOMIC_RELAXED, __HIP_MEMORY_SCOPE_AGENT); }
; __device__ __forceinline__ unsigned xb_add(unsigned* p, unsigned v) { return __hip_atomic_fetch_add(p, v, __ATOMIC_RELAXED, __HIP_MEMORY_SCOPE_AGENT); }
; #define XB_SPIN(cond, bar) do { unsigned _sp = 0; while (cond) { __builtin_amdgcn_s_sleep(1); \
;     if ((++_sp & 255u) == 0u) { if (xb_ld(&(bar)[XB_TMO])) break; if (_sp > XB_SPIN_CAP) { atomicAdd(&(bar)[XB_TMO], 1u); break; } } } } while (0)
; __device__ __forceinline__ void xcd_barrier(const XcdBarrier& b) {
;     ...
;         const unsigned old = xb_add(&bar[XB_XSUB(b.x)], 1u);
;         const unsigned gen = old / nloc;
;         if (old + 1u == (gen + 1u) * nloc) {
;             __builtin_amdgcn_fence(__ATOMIC_RELEASE, "agent");
;             asm volatile("s_waitcnt vmcnt(0)" ::: "memory");
;             const unsigned og = xb_add(&bar[XB_TOP], 1u);
;             const unsigned tg = og / nx;
;             if (og + 1u == (tg + 1u) * nx) xb_add(&bar[XB_TOPGEN], 1u);
;             else XB_SPIN(xb_ld(&bar[XB_TOPGEN]) == tg, bar);
;             __builtin_amdgcn_fence(__ATOMIC_ACQUIRE, "agent");
;             xb_add(&bar[XB_XGEN(b.x)], 1u);
;             asm volatile("s_waitcnt vmcnt(0)" ::: "memory");
.LBB0_528:
	s_or_b64 exec, exec, s[10:11]
	s_mov_b64 s[10:11], exec
	v_mbcnt_lo_u32_b32 v0, s10, 0
	v_mbcnt_hi_u32_b32 v0, s11, v0
	v_cmp_eq_u32_e32 vcc, 0, v0
	s_waitcnt vmcnt(0)
	buffer_inv sc1
	s_and_saveexec_b64 s[12:13], vcc
	s_cbranch_execz .LBB0_530
	s_bcnt1_i32_b64 s10, s[10:11]
	v_mov_b32_e32 v0, s10
.LBB0_530:
	s_or_b64 exec, exec, s[12:13]
	s_waitcnt vmcnt(0)

; __device__ __forceinline__ unsigned xb_ld(unsigned* p)              { return __hip_atomic_load(p, __ATOMIC_RELAXED, __HIP_MEMORY_SCOPE_AGENT); }
; __device__ __forceinline__ unsigned xb_add(unsigned* p, unsigned v) { return __hip_atomic_fetch_add(p, v, __ATOMIC_RELAXED, __HIP_MEMORY_SCOPE_AGENT); }
; #define XB_SPIN(cond, bar) do { unsigned _sp = 0; while (cond) { __builtin_amdgcn_s_sleep(1); \
;     if ((++_sp & 255u) == 0u) { if (xb_ld(&(bar)[XB_TMO])) break; if (_sp > XB_SPIN_CAP) { atomicAdd(&(bar)[XB_TMO], 1u); break; } } } } while (0)
; __device__ __forceinline__ void xcd_barrier(const XcdBarrier& b) {
;     ...
;         const unsigned old = xb_add(&bar[XB_XSUB(b.x)], 1u);
;         const unsigned gen = old / nloc;
;         if (old + 1u == (gen + 1u) * nloc) {
;             __builtin_amdgcn_fence(__ATOMIC_RELEASE, "agent");
;             asm volatile("s_waitcnt vmcnt(0)" ::: "memory");
;             const unsigned og = xb_add(&bar[XB_TOP], 1u);
;             const unsigned tg = og / nx;
;             if (og + 1u == (tg + 1u) * nx) xb_add(&bar[XB_TOPGEN], 1u);
;             else XB_SPIN(xb_ld(&bar[XB_TOPGEN]) == tg, bar);
;             __builtin_amdgcn_fence(__ATOMIC_ACQUIRE, "agent");
;             xb_add(&bar[XB_XGEN(b.x)], 1u);
;             asm volatile("s_waitcnt vmcnt(0)" ::: "memory");
.LBB0_625:
	s_or_b64 exec, exec, s[8:9]
	s_mov_b64 s[8:9], exec
	v_mbcnt_lo_u32_b32 v0, s8, 0
	v_mbcnt_hi_u32_b32 v0, s9, v0
	v_cmp_eq_u32_e32 vcc, 0, v0
	s_waitcnt vmcnt(0)
	buffer_inv sc1
	s_and_saveexec_b64 s[10:11], vcc
	s_cbranch_execz .LBB0_627
	s_bcnt1_i32_b64 s8, s[8:9]
	v_mov_b32_e32 v0, s8
.LBB0_627:
	s_or_b64 exec, exec, s[10:11]
	s_waitcnt vmcnt(0)

; __device__ __forceinline__ unsigned xb_ld(unsigned* p)              { return __hip_atomic_load(p, __ATOMIC_RELAXED, __HIP_MEMORY_SCOPE_AGENT); }
; __device__ __forceinline__ unsigned xb_add(unsigned* p, unsigned v) { return __hip_atomic_fetch_add(p, v, __ATOMIC_RELAXED, __HIP_MEMORY_SCOPE_AGENT); }
; #define XB_SPIN(cond, bar) do { unsigned _sp = 0; while (cond) { __builtin_amdgcn_s_sleep(1); \
;     if ((++_sp & 255u) == 0u) { if (xb_ld(&(bar)[XB_TMO])) break; if (_sp > XB_SPIN_CAP) { atomicAdd(&(bar)[XB_TMO], 1u); break; } } } } while (0)
; __device__ __forceinline__ void xcd_barrier(const XcdBarrier& b) {
;     ...
;         const unsigned old = xb_add(&bar[XB_XSUB(b.x)], 1u);
;         const unsigned gen = old / nloc;
;         if (old + 1u == (gen + 1u) * nloc) {
;             __builtin_amdgcn_fence(__ATOMIC_RELEASE, "agent");
;             asm volatile("s_waitcnt vmcnt(0)" ::: "memory");
;             const unsigned og = xb_add(&bar[XB_TOP], 1u);
;             const unsigned tg = og / nx;
;             if (og + 1u == (tg + 1u) * nx) xb_add(&bar[XB_TOPGEN], 1u);
;             else XB_SPIN(xb_ld(&bar[XB_TOPGEN]) == tg, bar);
;             __builtin_amdgcn_fence(__ATOMIC_ACQUIRE, "agent");
;             xb_add(&bar[XB_XGEN(b.x)], 1u);
;             asm volatile("s_waitcnt vmcnt(0)" ::: "memory");
.LBB0_687:
	s_or_b64 exec, exec, s[8:9]
	s_mov_b64 s[8:9], exec
	v_mbcnt_lo_u32_b32 v0, s8, 0
	v_mbcnt_hi_u32_b32 v0, s9, v0
	v_cmp_eq_u32_e32 vcc, 0, v0
	s_waitcnt vmcnt(0)
	buffer_inv sc1
	s_and_saveexec_b64 s[10:11], vcc
	s_cbranch_execz .LBB0_689
	s_bcnt1_i32_b64 s8, s[8:9]
	v_mov_b32_e32 v0, s8
.LBB0_689:
	s_or_b64 exec, exec, s[10:11]
	s_waitcnt vmcnt(0)

; __device__ __forceinline__ unsigned xb_ld(unsigned* p)              { return __hip_atomic_load(p, __ATOMIC_RELAXED, __HIP_MEMORY_SCOPE_AGENT); }
; __device__ __forceinline__ unsigned xb_add(unsigned* p, unsigned v) { return __hip_atomic_fetch_add(p, v, __ATOMIC_RELAXED, __HIP_MEMORY_SCOPE_AGENT); }
; #define XB_SPIN(cond, bar) do { unsigned _sp = 0; while (cond) { __builtin_amdgcn_s_sleep(1); \
;     if ((++_sp & 255u) == 0u) { if (xb_ld(&(bar)[XB_TMO])) break; if (_sp > XB_SPIN_CAP) { atomicAdd(&(bar)[XB_TMO], 1u); break; } } } } while (0)
; __device__ __forceinline__ void xcd_barrier(const XcdBarrier& b) {
;     ...
;         const unsigned old = xb_add(&bar[XB_XSUB(b.x)], 1u);
;         const unsigned gen = old / nloc;
;         if (old + 1u == (gen + 1u) * nloc) {
;             __builtin_amdgcn_fence(__ATOMIC_RELEASE, "agent");
;             asm volatile("s_waitcnt vmcnt(0)" ::: "memory");
;             const unsigned og = xb_add(&bar[XB_TOP], 1u);
;             const unsigned tg = og / nx;
;             if (og + 1u == (tg + 1u) * nx) xb_add(&bar[XB_TOPGEN], 1u);
;             else XB_SPIN(xb_ld(&bar[XB_TOPGEN]) == tg, bar);
;             __builtin_amdgcn_fence(__ATOMIC_ACQUIRE, "agent");
;             xb_add(&bar[XB_XGEN(b.x)], 1u);
;             asm volatile("s_waitcnt vmcnt(0)" ::: "memory");
.LBB0_855:
	s_or_b64 exec, exec, s[8:9]
	s_mov_b64 s[8:9], exec
	v_mbcnt_lo_u32_b32 v0, s8, 0
	v_mbcnt_hi_u32_b32 v0, s9, v0
	v_cmp_eq_u32_e32 vcc, 0, v0
	s_waitcnt vmcnt(0)
	buffer_inv sc1
	s_and_saveexec_b64 s[10:11], vcc
	s_cbranch_execz .LBB0_857
	s_bcnt1_i32_b64 s8, s[8:9]
	v_mov_b32_e32 v0, s8
.LBB0_857:
	s_or_b64 exec, exec, s[10:11]
	s_waitcnt vmcnt(0)

; __device__ __forceinline__ unsigned xb_ld(unsigned* p)              { return __hip_atomic_load(p, __ATOMIC_RELAXED, __HIP_MEMORY_SCOPE_AGENT); }
; __device__ __forceinline__ unsigned xb_add(unsigned* p, unsigned v) { return __hip_atomic_fetch_add(p, v, __ATOMIC_RELAXED, __HIP_MEMORY_SCOPE_AGENT); }
; #define XB_SPIN(cond, bar) do { unsigned _sp = 0; while (cond) { __builtin_amdgcn_s_sleep(1); \
;     if ((++_sp & 255u) == 0u) { if (xb_ld(&(bar)[XB_TMO])) break; if (_sp > XB_SPIN_CAP) { atomicAdd(&(bar)[XB_TMO], 1u); break; } } } } while (0)
; __device__ __forceinline__ void xcd_barrier(const XcdBarrier& b) {
;     ...
;         const unsigned old = xb_add(&bar[XB_XSUB(b.x)], 1u);
;         const unsigned gen = old / nloc;
;         if (old + 1u == (gen + 1u) * nloc) {
;             __builtin_amdgcn_fence(__ATOMIC_RELEASE, "agent");
;             asm volatile("s_waitcnt vmcnt(0)" ::: "memory");
;             const unsigned og = xb_add(&bar[XB_TOP], 1u);
;             const unsigned tg = og / nx;
;             if (og + 1u == (tg + 1u) * nx) xb_add(&bar[XB_TOPGEN], 1u);
;             else XB_SPIN(xb_ld(&bar[XB_TOPGEN]) == tg, bar);
;             __builtin_amdgcn_fence(__ATOMIC_ACQUIRE, "agent");
;             xb_add(&bar[XB_XGEN(b.x)], 1u);
;             asm volatile("s_waitcnt vmcnt(0)" ::: "memory");
.LBB0_1225:
	s_or_b64 exec, exec, s[12:13]
	s_mov_b64 s[12:13], exec
	v_mbcnt_lo_u32_b32 v0, s12, 0
	v_mbcnt_hi_u32_b32 v0, s13, v0
	v_cmp_eq_u32_e32 vcc, 0, v0
	s_waitcnt vmcnt(0)
	buffer_inv sc1
	s_and_saveexec_b64 s[16:17], vcc
	s_cbranch_execz .LBB0_1227
	s_bcnt1_i32_b64 s12, s[12:13]
	v_mov_b32_e32 v0, s12
.LBB0_1227:
	s_or_b64 exec, exec, s[16:17]
	s_waitcnt vmcnt(0)

; __device__ __forceinline__ unsigned xb_ld(unsigned* p)              { return __hip_atomic_load(p, __ATOMIC_RELAXED, __HIP_MEMORY_SCOPE_AGENT); }
; __device__ __forceinline__ unsigned xb_add(unsigned* p, unsigned v) { return __hip_atomic_fetch_add(p, v, __ATOMIC_RELAXED, __HIP_MEMORY_SCOPE_AGENT); }
; #define XB_SPIN(cond, bar) do { unsigned _sp = 0; while (cond) { __builtin_amdgcn_s_sleep(1); \
;     if ((++_sp & 255u) == 0u) { if (xb_ld(&(bar)[XB_TMO])) break; if (_sp > XB_SPIN_CAP) { atomicAdd(&(bar)[XB_TMO], 1u); break; } } } } while (0)
; __device__ __forceinline__ void xcd_barrier(const XcdBarrier& b) {
;     ...
;         const unsigned old = xb_add(&bar[XB_XSUB(b.x)], 1u);
;         const unsigned gen = old / nloc;
;         if (old + 1u == (gen + 1u) * nloc) {
;             __builtin_amdgcn_fence(__ATOMIC_RELEASE, "agent");
;             asm volatile("s_waitcnt vmcnt(0)" ::: "memory");
;             const unsigned og = xb_add(&bar[XB_TOP], 1u);
;             const unsigned tg = og / nx;
;             if (og + 1u == (tg + 1u) * nx) xb_add(&bar[XB_TOPGEN], 1u);
;             else XB_SPIN(xb_ld(&bar[XB_TOPGEN]) == tg, bar);
;             __builtin_amdgcn_fence(__ATOMIC_ACQUIRE, "agent");
;             xb_add(&bar[XB_XGEN(b.x)], 1u);
;             asm volatile("s_waitcnt vmcnt(0)" ::: "memory");
.LBB0_1328:
	s_or_b64 exec, exec, s[16:17]
	s_mov_b64 s[16:17], exec
	v_mbcnt_lo_u32_b32 v0, s16, 0
	v_mbcnt_hi_u32_b32 v0, s17, v0
	v_cmp_eq_u32_e32 vcc, 0, v0
	s_waitcnt vmcnt(0)
	buffer_inv sc1
	s_and_saveexec_b64 s[18:19], vcc
	s_cbranch_execz .LBB0_1330
	s_bcnt1_i32_b64 s16, s[16:17]
	v_mov_b32_e32 v0, s16
.LBB0_1330:
	s_or_b64 exec, exec, s[18:19]
	s_waitcnt vmcnt(0)

; __device__ __forceinline__ unsigned xb_ld(unsigned* p)              { return __hip_atomic_load(p, __ATOMIC_RELAXED, __HIP_MEMORY_SCOPE_AGENT); }
; __device__ __forceinline__ unsigned xb_add(unsigned* p, unsigned v) { return __hip_atomic_fetch_add(p, v, __ATOMIC_RELAXED, __HIP_MEMORY_SCOPE_AGENT); }
; #define XB_SPIN(cond, bar) do { unsigned _sp = 0; while (cond) { __builtin_amdgcn_s_sleep(1); \
;     if ((++_sp & 255u) == 0u) { if (xb_ld(&(bar)[XB_TMO])) break; if (_sp > XB_SPIN_CAP) { atomicAdd(&(bar)[XB_TMO], 1u); break; } } } } while (0)
; __device__ __forceinline__ void xcd_barrier(const XcdBarrier& b) {
;     ...
;         const unsigned old = xb_add(&bar[XB_XSUB(b.x)], 1u);
;         const unsigned gen = old / nloc;
;         if (old + 1u == (gen + 1u) * nloc) {
;             __builtin_amdgcn_fence(__ATOMIC_RELEASE, "agent");
;             asm volatile("s_waitcnt vmcnt(0)" ::: "memory");
;             const unsigned og = xb_add(&bar[XB_TOP], 1u);
;             const unsigned tg = og / nx;
;             if (og + 1u == (tg + 1u) * nx) xb_add(&bar[XB_TOPGEN], 1u);
;             else XB_SPIN(xb_ld(&bar[XB_TOPGEN]) == tg, bar);
;             __builtin_amdgcn_fence(__ATOMIC_ACQUIRE, "agent");
;             xb_add(&bar[XB_XGEN(b.x)], 1u);
;             asm volatile("s_waitcnt vmcnt(0)" ::: "memory");
.LBB0_1396:
	s_or_b64 exec, exec, s[20:21]
	s_mov_b64 s[20:21], exec
	v_mbcnt_lo_u32_b32 v0, s20, 0
	v_mbcnt_hi_u32_b32 v0, s21, v0
	v_cmp_eq_u32_e32 vcc, 0, v0
	s_waitcnt vmcnt(0)
	buffer_inv sc1
	s_and_saveexec_b64 s[22:23], vcc
	s_cbranch_execz .LBB0_1398
	s_bcnt1_i32_b64 s20, s[20:21]
	v_mov_b32_e32 v0, s20
.LBB0_1398:
	s_or_b64 exec, exec, s[22:23]
	s_waitcnt vmcnt(0)

; __device__ __forceinline__ unsigned xb_ld(unsigned* p)              { return __hip_atomic_load(p, __ATOMIC_RELAXED, __HIP_MEMORY_SCOPE_AGENT); }
; __device__ __forceinline__ unsigned xb_add(unsigned* p, unsigned v) { return __hip_atomic_fetch_add(p, v, __ATOMIC_RELAXED, __HIP_MEMORY_SCOPE_AGENT); }
; #define XB_SPIN(cond, bar) do { unsigned _sp = 0; while (cond) { __builtin_amdgcn_s_sleep(1); \
;     if ((++_sp & 255u) == 0u) { if (xb_ld(&(bar)[XB_TMO])) break; if (_sp > XB_SPIN_CAP) { atomicAdd(&(bar)[XB_TMO], 1u); break; } } } } while (0)
; __device__ __forceinline__ void xcd_barrier(const XcdBarrier& b) {
;     ...
;         const unsigned old = xb_add(&bar[XB_XSUB(b.x)], 1u);
;         const unsigned gen = old / nloc;
;         if (old + 1u == (gen + 1u) * nloc) {
;             __builtin_amdgcn_fence(__ATOMIC_RELEASE, "agent");
;             asm volatile("s_waitcnt vmcnt(0)" ::: "memory");
;             const unsigned og = xb_add(&bar[XB_TOP], 1u);
;             const unsigned tg = og / nx;
;             if (og + 1u == (tg + 1u) * nx) xb_add(&bar[XB_TOPGEN], 1u);
;             else XB_SPIN(xb_ld(&bar[XB_TOPGEN]) == tg, bar);
;             __builtin_amdgcn_fence(__ATOMIC_ACQUIRE, "agent");
;             xb_add(&bar[XB_XGEN(b.x)], 1u);
;             asm volatile("s_waitcnt vmcnt(0)" ::: "memory");
.LBB0_1767:
	s_or_b64 exec, exec, s[10:11]
	s_mov_b64 s[10:11], exec
	v_mbcnt_lo_u32_b32 v0, s10, 0
	v_mbcnt_hi_u32_b32 v0, s11, v0
	v_cmp_eq_u32_e32 vcc, 0, v0
	s_waitcnt vmcnt(0)
	buffer_inv sc1
	s_and_saveexec_b64 s[14:15], vcc
	s_cbranch_execz .LBB0_1769
	s_bcnt1_i32_b64 s10, s[10:11]
	v_mov_b32_e32 v0, s10
.LBB0_1769:
	s_or_b64 exec, exec, s[14:15]
	s_waitcnt vmcnt(0)

; __device__ __forceinline__ unsigned xb_ld(unsigned* p)              { return __hip_atomic_load(p, __ATOMIC_RELAXED, __HIP_MEMORY_SCOPE_AGENT); }
; __device__ __forceinline__ unsigned xb_add(unsigned* p, unsigned v) { return __hip_atomic_fetch_add(p, v, __ATOMIC_RELAXED, __HIP_MEMORY_SCOPE_AGENT); }
; #define XB_SPIN(cond, bar) do { unsigned _sp = 0; while (cond) { __builtin_amdgcn_s_sleep(1); \
;     if ((++_sp & 255u) == 0u) { if (xb_ld(&(bar)[XB_TMO])) break; if (_sp > XB_SPIN_CAP) { atomicAdd(&(bar)[XB_TMO], 1u); break; } } } } while (0)
; __device__ __forceinline__ void xcd_barrier(const XcdBarrier& b) {
;     ...
;         const unsigned old = xb_add(&bar[XB_XSUB(b.x)], 1u);
;         const unsigned gen = old / nloc;
;         if (old + 1u == (gen + 1u) * nloc) {
;             __builtin_amdgcn_fence(__ATOMIC_RELEASE, "agent");
;             asm volatile("s_waitcnt vmcnt(0)" ::: "memory");
;             const unsigned og = xb_add(&bar[XB_TOP], 1u);
;             const unsigned tg = og / nx;
;             if (og + 1u == (tg + 1u) * nx) xb_add(&bar[XB_TOPGEN], 1u);
;             else XB_SPIN(xb_ld(&bar[XB_TOPGEN]) == tg, bar);
;             __builtin_amdgcn_fence(__ATOMIC_ACQUIRE, "agent");
;             xb_add(&bar[XB_XGEN(b.x)], 1u);
;             asm volatile("s_waitcnt vmcnt(0)" ::: "memory");
.LBB0_1890:
	s_bcnt1_i32_b64 s8, s[8:9]
	v_mov_b32_e32 v0, s8
	s_getpc_b64 s[98:99]
